# P7 GLU GEMM moved onto the S5-output workgroups behind a counter barrier, overlapping P6 tail; seam 6 global barrier removed
# speedup vs baseline: 1.0078x; 1.0078x over previous
; #define LAS __attribute__((address_space(3)))
; #define OPAQUE_TID() int tid = threadIdx.x; asm volatile("" : "+v"(tid)); const int lane = tid & 63; const int wave = __builtin_amdgcn_readfirstlane(tid >> 6); (void)lane; (void)wave
; __global__ void __launch_bounds__(NWAVES * 64, 2) mega_fwd(Args args) {
;     ...
;         if (bx >= 64 && bx < 128) {
;             OPAQUE_TID(); LAS float* scr = (LAS float*)(lds + wave * 16384);
;             constexpr int J_GU = (DM / 64) * (FF / 64), J_D = (FF / 64) * (DM / 64), J_GLU = (512 / 64) * (512 / 64), J_BR = (512 / 64) * (DM / 64), J_SQ = (DM / 64) * (DM / 64), J_PP = (PLE / 64) * (DM / 64);
;             for (int it = (bx - 64) * NWAVES + wave; it < 2 * J_GU + J_D + J_GLU + 2 * J_BR + 2 * J_SQ + J_PP; it += 64 * NWAVES) { int r = it;
;                 if (r < J_GLU) { p0_transpose_item(args.in[18], 512, 512, Wglu, nullptr, 0, scr, r, lane); continue; } r -= J_GLU;
;                 if (r < J_BR) { p0_transpose_item(args.in[20], 512, DM, Wab, nullptr, 0, scr, r, lane); continue; } r -= J_BR;
;                 if (r < J_BR) { p0_transpose_item(args.in[21], 512, DM, Wsb, nullptr, 0, scr, r, lane); continue; } r -= J_BR;
;                 if (r < J_SQ) { p0_transpose_item(args.in[22], DM, DM, Wout, nullptr, 0, scr, r, lane); continue; } r -= J_SQ;
;                 if (r < J_GU) { p0_transpose_item(args.in[24], DM, FF, W2gu, args.in[23], 1, scr, r, lane); continue; } r -= J_GU;
;                 if (r < J_GU) { p0_transpose_item(args.in[25], DM, FF, W2gu, args.in[23], 2, scr, r, lane); continue; } r -= J_GU;
;                 if (r < J_D) { p0_transpose_item(args.in[26], FF, DM, W2d, nullptr, 0, scr, r, lane); continue; } r -= J_D;
;                 if (r < J_SQ) { p0_transpose_item(args.in[28], DM, DM, Wpg, args.in[27], 0, scr, r, lane); continue; } r -= J_SQ;
;                 p0_transpose_item(args.in[29], PLE, DM, Wpp, nullptr, 0, scr, r, lane); }
;             __syncthreads(); }
;         if (bx >= 128) {
;             if (threadIdx.x == 0) { unsigned sp = 0; while (__hip_atomic_load(scan_done, __ATOMIC_RELAXED, __HIP_MEMORY_SCOPE_AGENT) < 64u && ++sp < (1u << 22)) __builtin_amdgcn_s_sleep(2);
;                 __builtin_amdgcn_fence(__ATOMIC_ACQUIRE, "agent"); asm volatile("s_waitcnt vmcnt(0)" ::: "memory"); }
;             __syncthreads();
.LBB0_916:
	s_waitcnt vmcnt(0)
	s_barrier
	s_and_saveexec_b64 s[0:1], s[74:75]
	s_cbranch_execz .Lconv_arr_done
	buffer_wbl2 sc1
	s_waitcnt vmcnt(0)
	v_readlane_b32 s2, v252, 26
	v_readlane_b32 s3, v252, 27
	v_mov_b32_e32 v1, 0x4000
	v_mov_b32_e32 v2, 1
	s_nop 4
	global_atomic_add v1, v2, s[2:3]
.Lconv_arr_done:
	s_or_b64 exec, exec, s[0:1]
.LBB0_917:
	v_readlane_b32 s6, v252, 24
	s_cmpk_lt_i32 s88, 0x80
	v_readlane_b32 s7, v252, 25
	s_cbranch_scc1 .LBB0_955
	s_and_saveexec_b64 s[0:1], s[74:75]
	s_cbranch_execz .LBB0_931
	v_readlane_b32 s2, v252, 26
	v_mov_b32_e32 v1, 0
	v_readlane_b32 s3, v252, 27
	s_nop 4
	global_load_dword v2, v1, s[2:3] sc1
	s_waitcnt vmcnt(0)
	v_cmp_lt_u32_e32 vcc, 63, v2
	s_cbranch_vccnz .LBB0_930
	s_mov_b32 s4, 0x3ffff8
	s_branch .LBB0_922

; __device__ __forceinline__ unsigned xb_ld(unsigned* p)              { return __hip_atomic_load(p, __ATOMIC_RELAXED, __HIP_MEMORY_SCOPE_AGENT); }
; __device__ __forceinline__ unsigned xb_add(unsigned* p, unsigned v) { return __hip_atomic_fetch_add(p, v, __ATOMIC_RELAXED, __HIP_MEMORY_SCOPE_AGENT); }
; #define XB_SPIN(cond, bar) do { unsigned _sp = 0; while (cond) { __builtin_amdgcn_s_sleep(1); \
;     if ((++_sp & 255u) == 0u) { if (xb_ld(&(bar)[XB_TMO])) break; if (_sp > XB_SPIN_CAP) { atomicAdd(&(bar)[XB_TMO], 1u); break; } } } } while (0)
; __device__ __forceinline__ void xcd_barrier(const XcdBarrier& b) {
;     asm volatile("s_waitcnt vmcnt(0)" ::: "memory");
;     __syncthreads();
;     if (threadIdx.x == 0) {
;         unsigned* bar = b.bar;
;         __builtin_amdgcn_s_waitcnt(0);
;         unsigned nloc = b.st[0], nx = b.st[1];
;         if (nloc == 0u) { xcd_barrier_complete(bar, b.x, nloc, nx); b.st[0] = nloc; b.st[1] = nx; }
;         const unsigned old = xb_add(&bar[XB_XSUB(b.x)], 1u);
;         const unsigned gen = old / nloc;
;         if (old + 1u == (gen + 1u) * nloc) {
;             __builtin_amdgcn_fence(__ATOMIC_RELEASE, "agent");
;             asm volatile("s_waitcnt vmcnt(0)" ::: "memory");
;             const unsigned og = xb_add(&bar[XB_TOP], 1u);
;             const unsigned tg = og / nx;
;             if (og + 1u == (tg + 1u) * nx) xb_add(&bar[XB_TOPGEN], 1u);
;             else XB_SPIN(xb_ld(&bar[XB_TOPGEN]) == tg, bar);
;             __builtin_amdgcn_fence(__ATOMIC_ACQUIRE, "agent");
;             xb_add(&bar[XB_XGEN(b.x)], 1u);
;             asm volatile("s_waitcnt vmcnt(0)" ::: "memory");
;         } else {
;             XB_SPIN(xb_ld(&bar[XB_XGEN(b.x)]) == gen, bar);
;             __builtin_amdgcn_fence(__ATOMIC_ACQUIRE, "agent");
;             asm volatile("s_waitcnt vmcnt(0)" ::: "memory");
;         }
;     }
;     __syncthreads();
; }
; __global__ void __launch_bounds__(NWAVES * 64, 2) mega_fwd(Args args) {
;     ...
;     if (IN(7)) { pg8::Gemm g{ZB, Wglu, M, 512, 512, 512, 512, 0, 0, 1}; pg8::StaticOrder S; S.init(M, 512, 1, G, bx);
;         pg8::EpiGlu E{ZB, args.in[19], Z2B}; pg8::gemm_phase<pg8::EpiGlu, true>(lds, g, S, E); }
.LBB0_955:
	s_cmp_gt_i32 s85, 7
	s_cselect_b64 s[2:3], -1, 0
	s_and_b64 s[0:1], s[6:7], s[2:3]
	v_readlane_b32 s82, v252, 10
	s_andn2_b64 vcc, exec, s[0:1]
	v_readlane_b32 s83, v252, 11
	s_cbranch_vccnz .LBB0_1009
	s_cmpk_lt_i32 s88, 0x80
	s_cbranch_scc1 .LBB0_1009
	s_waitcnt vmcnt(0) lgkmcnt(0)
	s_barrier
	s_and_saveexec_b64 s[0:1], s[74:75]
	s_cbranch_execz .Lys_done
	buffer_wbl2 sc1
	s_waitcnt vmcnt(0)
	v_readlane_b32 s4, v252, 26
	v_readlane_b32 s5, v252, 27
	v_mov_b32_e32 v1, 0x4000
	v_mov_b32_e32 v2, 1
	s_mov_b32 s6, 0
	s_nop 4
	global_atomic_add v1, v2, s[4:5]
.Lys_spin:
	global_load_dword v3, v1, s[4:5] sc1
	s_waitcnt vmcnt(0)
	v_readfirstlane_b32 s7, v3
	s_nop 3
	s_cmpk_ge_u32 s7, 0xc0
	s_cbranch_scc1 .Lys_ok
	s_sleep 2
	s_add_i32 s6, s6, 1
	s_cmp_lt_u32 s6, 0x20000
	s_cbranch_scc1 .Lys_spin
.Lys_ok:
	buffer_inv sc1
	s_waitcnt vmcnt(0)
.Lys_done:
	s_or_b64 exec, exec, s[0:1]
	s_barrier
.LBB0_1009:
	s_cmp_lt_i32 s84, 8
	s_cselect_b64 s[4:5], -1, 0
	s_add_u32 s0, s64, 0x1000000
	s_addc_u32 s1, s65, 0
	s_and_b64 s[4:5], s[4:5], s[2:3]
	s_andn2_b64 vcc, exec, s[4:5]
	s_cbranch_vccnz .LBB0_1034
	v_mov_b32_e32 v10, v0
	s_cmpk_lt_i32 s88, 0x80
	v_readfirstlane_b32 s6, v10
	s_cbranch_scc1 .LBB0_1034
	s_addk_i32 s88, 0xff80
	s_ashr_i32 s19, s88, 31
	s_lshr_b32 s2, s19, 29
	s_add_i32 s7, s88, s2
	s_and_b32 s2, s7, -8
	s_sub_i32 s9, s88, s2
	s_cmp_gt_i32 s9, -1
	s_cbranch_scc0 .LBB0_1013
	s_lshl_b32 s8, s9, 4
	s_cbranch_execz .LBB0_1014
	s_branch .LBB0_1015

; __global__ void __launch_bounds__(NWAVES * 64, 2) mega_fwd(Args args) {
;     ...
;     if (IN(7)) { pg8::Gemm g{ZB, Wglu, M, 512, 512, 512, 512, 0, 0, 1}; pg8::StaticOrder S; S.init(M, 512, 1, G, bx);
;         pg8::EpiGlu E{ZB, args.in[19], Z2B}; pg8::gemm_phase<pg8::EpiGlu, true>(lds, g, S, E); }
.LBB0_1033:
	s_waitcnt vmcnt(0)
	s_barrier
	s_addk_i32 s88, 0x80
